# v24 plus the lora block-matrix writer skipping the chunks that the K-trimmed lora GEMM never reads
# speedup vs baseline: 1.0103x; 1.0011x over previous
.Llora_loop:
	s_cmp_lt_u32 s50, 0x30000
	s_cbranch_scc0 .Llora_done
	s_lshr_b32 s51, s50, 12
	s_and_b32 s56, s50, 0xfff
	s_lshr_b32 s57, s56, 10
	s_and_b32 s58, s56, 0x3ff
	s_cmp_lt_u32 s57, 2
	s_cbranch_scc0 .Llora_tr2
	s_cmp_lt_u32 s51, 16
	s_cbranch_scc0 .Llora_next
	s_branch .Llora_trok
.Llora_tr2:
	s_cmp_eq_u32 s57, 2
	s_cbranch_scc0 .Llora_tr3
	s_cmp_lt_u32 s51, 16
	s_cbranch_scc1 .Llora_next
	s_branch .Llora_trok
.Llora_tr3:
	s_cmp_eq_u32 s22, 0
	s_cbranch_scc1 .Llora_next
	s_cmp_lt_u32 s51, 32
	s_cbranch_scc1 .Llora_next
.Llora_trok:
	s_mul_i32 s59, s56, 0x300
	s_lshl_b32 s60, s51, 4
	s_add_u32 s59, s59, s60
	s_add_u32 s60, s26, s59
	s_addc_u32 s61, s27, 0
	s_cmp_eq_u32 s57, 0
	s_cbranch_scc0 .Llora_t1
	s_cmp_lt_u32 s51, 8
	s_cbranch_scc0 .Llora_zero
	s_mov_b64 s[62:63], s[0:1]
	s_lshl_b32 s64, s51, 3
	s_branch .Llora_load

.Llora_next:
	s_add_u32 s50, s50, s82
	s_branch .Llora_loop
